# k56: k42 + unit-completion counter, one atomic per chain workgroup after a workgroup barrier, count prefetched with the side barrier's arrival atomic
# speedup vs baseline: 1.0030x; 1.0025x over previous
; __device__ __forceinline__ unsigned xb_add(unsigned* p, unsigned v) { return __hip_atomic_fetch_add(p, v, __ATOMIC_RELAXED, __HIP_MEMORY_SCOPE_AGENT); }
; __device__ __forceinline__ void xcd_barrier(const XcdBarrier& b) {
;     ...
;         unsigned nloc = b.st[0], nx = b.st[1];
;         if (nloc == 0u) { xcd_barrier_complete(bar, b.x, b.gsz, nloc, nx); b.st[0] = nloc; b.st[1] = nx; }
;         const unsigned old = xb_add(&bar[XB_XSUB(b.x)], 1u);
;         const unsigned gen = old / nloc;
;         if (old + 1u == (gen + 1u) * nloc) {
.LBB0_170:
	s_mov_b64 s[6:7], exec
	s_lshl_b32 s4, s10, 8
	v_mbcnt_lo_u32_b32 v1, s6, 0
	s_add_u32 s4, s48, s4
	v_readlane_b32 s5, v251, 27
	v_mbcnt_hi_u32_b32 v1, s7, v1
	s_addc_u32 s5, s5, 0
	v_cmp_eq_u32_e32 vcc, 0, v1
	s_and_saveexec_b64 s[8:9], vcc
	s_cbranch_execz .LBB0_172
	s_bcnt1_i32_b64 s6, s[6:7]
	v_mov_b32_e32 v4, s6
	global_atomic_add v4, v208, v4, s[4:5] offset:1024 sc0
	s_mov_b32 s43, 0
	s_cmp_eq_u32 s3, 4
	s_cbranch_scc1 .Lcp_l0
	s_cmp_eq_u32 s3, 13
	s_cbranch_scc0 .Lcp_done
	s_movk_i32 s43, 0x40
	s_add_u32 s44, s94, 0x8040
	s_branch .Lcp_go
.Lcp_l0:
	s_movk_i32 s43, 0x20
	s_add_u32 s44, s94, 0x8000

; __device__ __forceinline__ void mixer_layer0(Frame& F) {
;     const float* rot = (const float*)(F.ws + WS_ROT);
;     int bid = blockIdx.x; asm volatile("" : "+s"(bid));
;     if (bid < 64) { const int u = bid, ty = u >> 5, bh = u & 31; if (ty == 0) mix_sg_unit<0>(F, bh >> 2, bh & 3, 0, rot); else mix_sg_unit<1>(F, bh >> 2, bh & 3, 0, rot); return; }
; #pragma unroll 1
;     for (int u = bid - 64; u < 1024 + 8; u += F.G - 64) {
;         int ty, bh, mode;
;         if (u < 1024) { ty = u >> 9; bh = u & 511; mode = 1; } else { ty = (u - 1024) >> 2; bh = (u - 1024) & 3; mode = 2; }
;         if (ty == 0) mix_sg_unit<0>(F, bh >> 2, bh & 3, mode, rot); else mix_sg_unit<1>(F, bh >> 2, bh & 3, mode, rot);
;     }
.LBB0_766:
	s_cmp_gt_i32 s78, 63
	s_cbranch_scc1 .Lsig0_skip
	s_waitcnt vmcnt(0)
	s_barrier
	v_readlane_b32 s98, v251, 3
	v_readlane_b32 s99, v251, 4
	s_mov_b64 s[44:45], exec
	s_and_b64 exec, exec, s[98:99]
	s_add_u32 s100, s94, 0x8000
	s_addc_u32 s101, s95, 0
	global_atomic_add v3, v210, s[100:101]
	s_mov_b64 exec, s[44:45]

; __device__ __forceinline__ void mixer_layer1(Frame& F) {
;     int bid = blockIdx.x; asm volatile("" : "+s"(bid));
;     if (bid < 64) { mix_hg_unit(F, bid >> 3, bid & 7, 0); return; }
; #pragma unroll 1
;     for (int u = bid - 64; u < 1024 + 8; u += F.G - 64) {
;         if (u < 1024) mix_hg_unit(F, u >> 3, u & 7, 1); else mix_hg_unit(F, 0, u - 1024, 2);
;     }
.LBB0_874:
	s_cmp_gt_i32 s0, 63
	s_cbranch_scc1 .Lsig1_skip
	s_waitcnt vmcnt(0)
	s_barrier
	v_readlane_b32 s98, v251, 3
	v_readlane_b32 s99, v251, 4
	s_mov_b64 s[44:45], exec
	s_and_b64 exec, exec, s[98:99]
	s_add_u32 s100, s94, 0x8040
	s_addc_u32 s101, s95, 0
	global_atomic_add v3, v210, s[100:101]
	s_mov_b64 exec, s[44:45]
